# write-through (sc1) on the widened P2/P3/P5 epilogue stores so the grid barriers' L2 writeback has less to flush
# speedup vs baseline: 1.0043x; 1.0043x over previous
.LBB0_263:
	v_mbcnt_lo_u32_b32 v242, -1, 0
	v_mbcnt_hi_u32_b32 v242, -1, v242
	v_bfe_u32 v242, v242, 4, 1
	v_mul_u32_u24_e32 v242, 24, v242
	v_mov_b32_e32 v243, 0
	v_lshl_or_b32 v140, s77, 8, v180
	v_lshl_add_u32 v184, s76, 8, v176
	v_ashrrev_i32_e32 v141, 31, v140
	v_lshlrev_b64 v[186:187], 1, v[140:141]
	v_ashrrev_i32_e32 v185, 31, v184
	v_lshl_add_u64 v[142:143], s[34:35], 0, v[186:187]
	v_lshlrev_b64 v[144:145], 12, v[184:185]
	v_lshl_add_u64 v[146:147], v[142:143], 0, v[144:145]
	v_lshl_add_u64 v[252:253], v[146:147], 0, v[242:243]
	global_load_dwordx4 v[208:211], v[252:253], off
	v_lshl_add_u64 v[252:253], v[146:147], 0, v[242:243]
	global_load_dwordx4 v[212:215], v[252:253], off offset:256
	v_or_b32_e32 v146, 16, v184
	v_or_b32_e32 v148, 32, v184
	v_or_b32_e32 v150, 48, v184
	v_ashrrev_i32_e32 v147, 31, v146
	v_ashrrev_i32_e32 v149, 31, v148
	v_ashrrev_i32_e32 v151, 31, v150
	v_lshlrev_b64 v[166:167], 12, v[146:147]
	v_lshlrev_b64 v[156:157], 12, v[148:149]
	v_lshlrev_b64 v[146:147], 12, v[150:151]
	v_lshl_add_u64 v[148:149], v[142:143], 0, v[166:167]
	v_lshl_add_u64 v[150:151], v[142:143], 0, v[156:157]
	v_lshl_add_u64 v[196:197], v[142:143], 0, v[146:147]
	v_lshl_add_u64 v[252:253], v[148:149], 0, v[242:243]
	global_load_dwordx4 v[216:219], v[252:253], off
	v_lshl_add_u64 v[252:253], v[148:149], 0, v[242:243]
	global_load_dwordx4 v[220:223], v[252:253], off offset:256
	v_lshl_add_u64 v[252:253], v[150:151], 0, v[242:243]
	global_load_dwordx4 v[224:227], v[252:253], off
	v_lshl_add_u64 v[252:253], v[150:151], 0, v[242:243]
	global_load_dwordx4 v[228:231], v[252:253], off offset:256
	v_lshl_add_u64 v[252:253], v[196:197], 0, v[242:243]
	global_load_dwordx4 v[244:247], v[252:253], off
	s_nop 0
	v_lshl_add_u64 v[252:253], v[196:197], 0, v[242:243]
	global_load_dwordx4 v[248:251], v[252:253], off offset:256
	v_lshl_add_u64 v[196:197], s[34:35], 0, v[144:145]
	v_lshl_add_u64 v[186:187], v[196:197], 0, v[186:187]
	s_waitcnt vmcnt(0)
	v_permlane16_swap_b32 v208, v210
	v_permlane16_swap_b32 v209, v211
	v_lshlrev_b32_e32 v196, 16, v208
	v_and_b32_e32 v197, 0xffff0000, v208
	v_lshlrev_b32_e32 v188, 16, v209
	v_and_b32_e32 v189, 0xffff0000, v209
	v_lshlrev_b32_e32 v198, 16, v210
	v_and_b32_e32 v199, 0xffff0000, v210
	v_lshlrev_b32_e32 v190, 16, v211
	v_and_b32_e32 v191, 0xffff0000, v211
	v_permlane16_swap_b32 v212, v214
	v_permlane16_swap_b32 v213, v215
	v_lshlrev_b32_e32 v200, 16, v212
	v_and_b32_e32 v201, 0xffff0000, v212
	v_lshlrev_b32_e32 v192, 16, v213
	v_and_b32_e32 v193, 0xffff0000, v213
	v_lshlrev_b32_e32 v202, 16, v214
	v_and_b32_e32 v203, 0xffff0000, v214
	v_lshlrev_b32_e32 v194, 16, v215
	v_and_b32_e32 v195, 0xffff0000, v215
	v_pk_fma_f32 v[126:127], v[126:127], 0.5, v[188:189] op_sel_hi:[1,0,1]
	v_pk_fma_f32 v[124:125], v[124:125], 0.5, v[196:197] op_sel_hi:[1,0,1]
	v_pk_fma_f32 v[122:123], v[122:123], 0.5, v[190:191] op_sel_hi:[1,0,1]
	v_pk_fma_f32 v[120:121], v[120:121], 0.5, v[198:199] op_sel_hi:[1,0,1]
	v_pk_fma_f32 v[118:119], v[118:119], 0.5, v[192:193] op_sel_hi:[1,0,1]
	v_pk_fma_f32 v[116:117], v[116:117], 0.5, v[200:201] op_sel_hi:[1,0,1]
	v_pk_fma_f32 v[188:189], v[114:115], 0.5, v[194:195] op_sel_hi:[1,0,1]
	v_mul_f32_e32 v190, v125, v125
	v_mul_f32_e32 v191, v127, v127
	v_cvt_pk_bf16_f32 v232, v124, v125
	v_cvt_pk_bf16_f32 v233, v126, v127
	v_mul_f32_e32 v125, v121, v121
	v_mul_f32_e32 v127, v123, v123
	v_pk_fma_f32 v[112:113], v[112:113], 0.5, v[202:203] op_sel_hi:[1,0,1]
	v_mul_f32_e32 v192, v117, v117
	v_mul_f32_e32 v193, v119, v119
	v_fmac_f32_e32 v190, v124, v124
	v_fmac_f32_e32 v191, v126, v126
	v_fmac_f32_e32 v125, v120, v120
	v_fmac_f32_e32 v127, v122, v122
	v_mul_f32_e32 v194, v113, v113
	v_mul_f32_e32 v195, v189, v189
	v_cvt_pk_bf16_f32 v234, v120, v121
	v_fmac_f32_e32 v192, v116, v116
	v_fmac_f32_e32 v193, v118, v118
	v_add_f32_e32 v120, v190, v191
	v_add_f32_e32 v121, v125, v127
	v_cvt_pk_bf16_f32 v235, v122, v123
	v_fmac_f32_e32 v194, v112, v112
	v_fmac_f32_e32 v195, v188, v188
	v_add_f32_e32 v122, v192, v193
	v_add_f32_e32 v120, v120, v121
	v_add_f32_e32 v120, v120, v122
	v_add_f32_e32 v121, v194, v195
	v_add_f32_e32 v120, v120, v121
	ds_bpermute_b32 v121, v178, v120
	s_nop 1
	v_permlane16_swap_b32 v232, v234
	v_permlane16_swap_b32 v233, v235
	v_lshl_add_u64 v[240:241], v[186:187], 0, v[242:243]
	global_store_dwordx4 v[240:241], v[232:235], off sc1
	v_cvt_pk_bf16_f32 v236, v116, v117
	v_cvt_pk_bf16_f32 v237, v118, v119
	s_waitcnt lgkmcnt(0)
	v_add_f32_e32 v114, v120, v121
	ds_bpermute_b32 v115, v179, v114
	v_cvt_pk_bf16_f32 v238, v112, v113
	v_cvt_pk_bf16_f32 v239, v188, v189
	s_nop 1
	v_permlane16_swap_b32 v236, v238
	v_permlane16_swap_b32 v237, v239
	v_lshl_add_u64 v[240:241], v[186:187], 0, v[242:243]
	global_store_dwordx4 v[240:241], v[236:239], off offset:256 sc1
	v_lshl_add_u64 v[112:113], v[184:185], 2, s[26:27]
	s_and_saveexec_b64 s[50:51], s[6:7]
	s_cbranch_execz .LBB0_265
	s_waitcnt lgkmcnt(0)
	v_add_f32_e32 v114, v114, v115
	global_atomic_add_f32 v[112:113], v114, off
.LBB0_265:
	s_or_b64 exec, exec, s[50:51]
	v_permlane16_swap_b32 v216, v218
	v_permlane16_swap_b32 v217, v219
	v_lshlrev_b32_e32 v114, 16, v216
	s_waitcnt lgkmcnt(0)
	v_and_b32_e32 v115, 0xffff0000, v216
	v_lshlrev_b32_e32 v116, 16, v217
	v_and_b32_e32 v117, 0xffff0000, v217
	v_pk_fma_f32 v[110:111], v[110:111], 0.5, v[116:117] op_sel_hi:[1,0,1]
	v_pk_fma_f32 v[108:109], v[108:109], 0.5, v[114:115] op_sel_hi:[1,0,1]
	v_mul_f32_e32 v115, v111, v111
	v_mul_f32_e32 v114, v109, v109
	v_lshlrev_b32_e32 v118, 16, v218
	v_and_b32_e32 v119, 0xffff0000, v218
	v_lshlrev_b32_e32 v120, 16, v219
	v_and_b32_e32 v121, 0xffff0000, v219
	v_fmac_f32_e32 v114, v108, v108
	v_fmac_f32_e32 v115, v110, v110
	v_cvt_pk_bf16_f32 v232, v108, v109
	v_cvt_pk_bf16_f32 v233, v110, v111
	v_lshl_add_u64 v[110:111], s[34:35], 0, v[166:167]
	v_lshl_add_u64 v[110:111], v[140:141], 1, v[110:111]
	v_pk_fma_f32 v[106:107], v[106:107], 0.5, v[120:121] op_sel_hi:[1,0,1]
	v_pk_fma_f32 v[104:105], v[104:105], 0.5, v[118:119] op_sel_hi:[1,0,1]
	v_permlane16_swap_b32 v220, v222
	v_permlane16_swap_b32 v221, v223
	v_lshlrev_b32_e32 v122, 16, v220
	v_and_b32_e32 v123, 0xffff0000, v220
	v_lshlrev_b32_e32 v124, 16, v221
	v_and_b32_e32 v125, 0xffff0000, v221
	v_mul_f32_e32 v108, v105, v105
	v_mul_f32_e32 v109, v107, v107
	v_fmac_f32_e32 v108, v104, v104
	v_fmac_f32_e32 v109, v106, v106
	v_pk_fma_f32 v[102:103], v[102:103], 0.5, v[124:125] op_sel_hi:[1,0,1]
	v_pk_fma_f32 v[100:101], v[100:101], 0.5, v[122:123] op_sel_hi:[1,0,1]
	v_add_f32_e32 v108, v108, v109
	v_cvt_pk_bf16_f32 v234, v104, v105
	v_mul_f32_e32 v105, v101, v101
	v_mul_f32_e32 v109, v103, v103
	v_add_f32_e32 v114, v114, v115
	v_fmac_f32_e32 v105, v100, v100
	v_fmac_f32_e32 v109, v102, v102
	v_lshlrev_b32_e32 v126, 16, v222
	v_and_b32_e32 v127, 0xffff0000, v222
	v_lshlrev_b32_e32 v168, 16, v223
	v_and_b32_e32 v169, 0xffff0000, v223
	v_add_f32_e32 v108, v114, v108
	v_add_f32_e32 v105, v105, v109
	v_add_f32_e32 v105, v108, v105
	v_pk_fma_f32 v[98:99], v[98:99], 0.5, v[168:169] op_sel_hi:[1,0,1]
	v_pk_fma_f32 v[108:109], v[96:97], 0.5, v[126:127] op_sel_hi:[1,0,1]
	v_mul_f32_e32 v97, v99, v99
	v_mul_f32_e32 v96, v109, v109
	v_fmac_f32_e32 v96, v108, v108
	v_fmac_f32_e32 v97, v98, v98
	v_add_f32_e32 v96, v96, v97
	v_add_f32_e32 v96, v105, v96
	ds_bpermute_b32 v97, v178, v96
	v_cvt_pk_bf16_f32 v235, v106, v107
	s_nop 1
	v_permlane16_swap_b32 v232, v234
	v_permlane16_swap_b32 v233, v235
	v_lshl_add_u64 v[240:241], v[110:111], 0, v[242:243]
	global_store_dwordx4 v[240:241], v[232:235], off sc1
	v_cvt_pk_bf16_f32 v236, v100, v101
	v_cvt_pk_bf16_f32 v237, v102, v103
	s_waitcnt lgkmcnt(0)
	v_add_f32_e32 v96, v96, v97
	ds_bpermute_b32 v97, v179, v96
	v_cvt_pk_bf16_f32 v238, v108, v109
	v_cvt_pk_bf16_f32 v239, v98, v99
	s_nop 1
	v_permlane16_swap_b32 v236, v238
	v_permlane16_swap_b32 v237, v239
	v_lshl_add_u64 v[240:241], v[110:111], 0, v[242:243]
	global_store_dwordx4 v[240:241], v[236:239], off offset:256 sc1
	s_and_saveexec_b64 s[50:51], s[6:7]
	s_cbranch_execz .LBB0_267
	s_waitcnt lgkmcnt(0)
	v_add_f32_e32 v96, v96, v97
	global_atomic_add_f32 v[112:113], v96, off offset:64
.LBB0_267:
	s_or_b64 exec, exec, s[50:51]
	v_permlane16_swap_b32 v224, v226
	v_permlane16_swap_b32 v225, v227
	v_lshlrev_b32_e32 v96, 16, v224
	s_waitcnt lgkmcnt(0)
	v_and_b32_e32 v97, 0xffff0000, v224
	v_lshlrev_b32_e32 v98, 16, v225
	v_and_b32_e32 v99, 0xffff0000, v225
	v_pk_fma_f32 v[94:95], v[94:95], 0.5, v[98:99] op_sel_hi:[1,0,1]
	v_pk_fma_f32 v[92:93], v[92:93], 0.5, v[96:97] op_sel_hi:[1,0,1]
	v_mul_f32_e32 v97, v95, v95
	v_mul_f32_e32 v96, v93, v93
	v_lshlrev_b32_e32 v100, 16, v226
	v_and_b32_e32 v101, 0xffff0000, v226
	v_lshlrev_b32_e32 v102, 16, v227
	v_and_b32_e32 v103, 0xffff0000, v227
	v_fmac_f32_e32 v96, v92, v92
	v_fmac_f32_e32 v97, v94, v94
	v_cvt_pk_bf16_f32 v232, v92, v93
	v_cvt_pk_bf16_f32 v233, v94, v95
	v_lshl_add_u64 v[94:95], s[34:35], 0, v[156:157]
	v_lshl_add_u64 v[94:95], v[140:141], 1, v[94:95]
	v_pk_fma_f32 v[90:91], v[90:91], 0.5, v[102:103] op_sel_hi:[1,0,1]
	v_pk_fma_f32 v[88:89], v[88:89], 0.5, v[100:101] op_sel_hi:[1,0,1]
	v_permlane16_swap_b32 v228, v230
	v_permlane16_swap_b32 v229, v231
	v_lshlrev_b32_e32 v104, 16, v228
	v_and_b32_e32 v105, 0xffff0000, v228
	v_lshlrev_b32_e32 v106, 16, v229
	v_and_b32_e32 v107, 0xffff0000, v229
	v_mul_f32_e32 v92, v89, v89
	v_mul_f32_e32 v93, v91, v91
	v_fmac_f32_e32 v92, v88, v88
	v_fmac_f32_e32 v93, v90, v90
	v_pk_fma_f32 v[86:87], v[86:87], 0.5, v[106:107] op_sel_hi:[1,0,1]
	v_pk_fma_f32 v[84:85], v[84:85], 0.5, v[104:105] op_sel_hi:[1,0,1]
	v_add_f32_e32 v92, v92, v93
	v_cvt_pk_bf16_f32 v234, v88, v89
	v_mul_f32_e32 v89, v85, v85
	v_mul_f32_e32 v93, v87, v87
	v_add_f32_e32 v96, v96, v97
	v_fmac_f32_e32 v89, v84, v84
	v_fmac_f32_e32 v93, v86, v86
	v_lshlrev_b32_e32 v108, 16, v230
	v_and_b32_e32 v109, 0xffff0000, v230
	v_lshlrev_b32_e32 v110, 16, v231
	v_and_b32_e32 v111, 0xffff0000, v231
	v_add_f32_e32 v92, v96, v92
	v_add_f32_e32 v89, v89, v93
	v_add_f32_e32 v89, v92, v89
	v_pk_fma_f32 v[82:83], v[82:83], 0.5, v[110:111] op_sel_hi:[1,0,1]
	v_pk_fma_f32 v[92:93], v[80:81], 0.5, v[108:109] op_sel_hi:[1,0,1]
	v_mul_f32_e32 v81, v83, v83
	v_mul_f32_e32 v80, v93, v93
	v_fmac_f32_e32 v80, v92, v92
	v_fmac_f32_e32 v81, v82, v82
	v_add_f32_e32 v80, v80, v81
	v_add_f32_e32 v80, v89, v80
	ds_bpermute_b32 v81, v178, v80
	v_cvt_pk_bf16_f32 v235, v90, v91
	s_nop 1
	v_permlane16_swap_b32 v232, v234
	v_permlane16_swap_b32 v233, v235
	v_lshl_add_u64 v[240:241], v[94:95], 0, v[242:243]
	global_store_dwordx4 v[240:241], v[232:235], off sc1
	v_cvt_pk_bf16_f32 v236, v84, v85
	v_cvt_pk_bf16_f32 v237, v86, v87
	s_waitcnt lgkmcnt(0)
	v_add_f32_e32 v80, v80, v81
	ds_bpermute_b32 v81, v179, v80
	v_cvt_pk_bf16_f32 v238, v92, v93
	v_cvt_pk_bf16_f32 v239, v82, v83
	s_nop 1
	v_permlane16_swap_b32 v236, v238
	v_permlane16_swap_b32 v237, v239
	v_lshl_add_u64 v[240:241], v[94:95], 0, v[242:243]
	global_store_dwordx4 v[240:241], v[236:239], off offset:256 sc1
	s_and_saveexec_b64 s[50:51], s[6:7]
	s_cbranch_execz .LBB0_269
	s_waitcnt lgkmcnt(0)
	v_add_f32_e32 v80, v80, v81
	global_atomic_add_f32 v[112:113], v80, off offset:128
.LBB0_269:
	s_or_b64 exec, exec, s[50:51]
	v_permlane16_swap_b32 v244, v246
	v_permlane16_swap_b32 v245, v247
	v_lshlrev_b32_e32 v80, 16, v244
	s_waitcnt lgkmcnt(0)
	v_and_b32_e32 v81, 0xffff0000, v244
	v_lshlrev_b32_e32 v82, 16, v245
	v_and_b32_e32 v83, 0xffff0000, v245
	v_pk_fma_f32 v[78:79], v[78:79], 0.5, v[82:83] op_sel_hi:[1,0,1]
	v_pk_fma_f32 v[76:77], v[76:77], 0.5, v[80:81] op_sel_hi:[1,0,1]
	v_mul_f32_e32 v81, v79, v79
	v_mul_f32_e32 v80, v77, v77
	v_lshlrev_b32_e32 v84, 16, v246
	v_and_b32_e32 v85, 0xffff0000, v246
	v_lshlrev_b32_e32 v86, 16, v247
	v_and_b32_e32 v87, 0xffff0000, v247
	v_fmac_f32_e32 v80, v76, v76
	v_fmac_f32_e32 v81, v78, v78
	v_cvt_pk_bf16_f32 v232, v76, v77
	v_cvt_pk_bf16_f32 v233, v78, v79
	v_lshl_add_u64 v[78:79], s[34:35], 0, v[146:147]
	v_lshl_add_u64 v[78:79], v[140:141], 1, v[78:79]
	v_pk_fma_f32 v[74:75], v[74:75], 0.5, v[86:87] op_sel_hi:[1,0,1]
	v_pk_fma_f32 v[72:73], v[72:73], 0.5, v[84:85] op_sel_hi:[1,0,1]
	v_permlane16_swap_b32 v248, v250
	v_permlane16_swap_b32 v249, v251
	v_lshlrev_b32_e32 v88, 16, v248
	v_and_b32_e32 v89, 0xffff0000, v248
	v_lshlrev_b32_e32 v90, 16, v249
	v_and_b32_e32 v91, 0xffff0000, v249
	v_mul_f32_e32 v76, v73, v73
	v_mul_f32_e32 v77, v75, v75
	v_fmac_f32_e32 v76, v72, v72
	v_fmac_f32_e32 v77, v74, v74
	v_pk_fma_f32 v[70:71], v[70:71], 0.5, v[90:91] op_sel_hi:[1,0,1]
	v_pk_fma_f32 v[68:69], v[68:69], 0.5, v[88:89] op_sel_hi:[1,0,1]
	v_add_f32_e32 v76, v76, v77
	v_cvt_pk_bf16_f32 v234, v72, v73
	v_mul_f32_e32 v73, v69, v69
	v_mul_f32_e32 v77, v71, v71
	v_add_f32_e32 v80, v80, v81
	v_fmac_f32_e32 v73, v68, v68
	v_fmac_f32_e32 v77, v70, v70
	v_lshlrev_b32_e32 v92, 16, v250
	v_and_b32_e32 v93, 0xffff0000, v250
	v_lshlrev_b32_e32 v94, 16, v251
	v_and_b32_e32 v95, 0xffff0000, v251
	v_add_f32_e32 v76, v80, v76
	v_add_f32_e32 v73, v73, v77
	v_add_f32_e32 v73, v76, v73
	v_pk_fma_f32 v[66:67], v[66:67], 0.5, v[94:95] op_sel_hi:[1,0,1]
	v_pk_fma_f32 v[76:77], v[64:65], 0.5, v[92:93] op_sel_hi:[1,0,1]
	v_mul_f32_e32 v65, v67, v67
	v_mul_f32_e32 v64, v77, v77
	v_fmac_f32_e32 v64, v76, v76
	v_fmac_f32_e32 v65, v66, v66
	v_add_f32_e32 v64, v64, v65
	v_add_f32_e32 v64, v73, v64
	ds_bpermute_b32 v65, v178, v64
	v_cvt_pk_bf16_f32 v235, v74, v75
	s_nop 1
	v_permlane16_swap_b32 v232, v234
	v_permlane16_swap_b32 v233, v235
	v_lshl_add_u64 v[240:241], v[78:79], 0, v[242:243]
	global_store_dwordx4 v[240:241], v[232:235], off sc1
	v_cvt_pk_bf16_f32 v236, v68, v69
	v_cvt_pk_bf16_f32 v237, v70, v71
	s_waitcnt lgkmcnt(0)
	v_add_f32_e32 v64, v64, v65
	ds_bpermute_b32 v65, v179, v64
	v_cvt_pk_bf16_f32 v238, v76, v77
	v_cvt_pk_bf16_f32 v239, v66, v67
	s_nop 1
	v_permlane16_swap_b32 v236, v238
	v_permlane16_swap_b32 v237, v239
	v_lshl_add_u64 v[240:241], v[78:79], 0, v[242:243]
	global_store_dwordx4 v[240:241], v[236:239], off offset:256 sc1
	s_and_saveexec_b64 s[50:51], s[6:7]
	s_cbranch_execz .LBB0_271
	s_waitcnt lgkmcnt(0)
	v_add_f32_e32 v64, v64, v65
	global_atomic_add_f32 v[112:113], v64, off offset:192
.LBB0_271:
	s_or_b64 exec, exec, s[50:51]
	s_mov_b64 s[50:51], 0x80000
	v_lshl_add_u64 v[94:95], v[144:145], 0, s[50:51]
	s_waitcnt lgkmcnt(0)
	v_lshl_add_u64 v[64:65], v[142:143], 0, v[94:95]
	v_lshl_add_u64 v[252:253], v[64:65], 0, v[242:243]
	global_load_dwordx4 v[208:211], v[252:253], off
	v_lshl_add_u64 v[252:253], v[64:65], 0, v[242:243]
	global_load_dwordx4 v[212:215], v[252:253], off offset:256
	s_mov_b64 s[50:51], 0x90000
	v_lshl_add_u64 v[74:75], v[144:145], 0, s[20:21]
	v_lshl_add_u64 v[64:65], v[144:145], 0, s[46:47]
	v_lshl_add_u64 v[84:85], v[144:145], 0, s[50:51]
	v_lshl_add_u64 v[66:67], v[142:143], 0, v[74:75]
	v_lshl_add_u64 v[86:87], v[142:143], 0, v[64:65]
	v_lshl_add_u64 v[104:105], v[142:143], 0, v[84:85]
	v_lshl_add_u64 v[252:253], v[66:67], 0, v[242:243]
	global_load_dwordx4 v[216:219], v[252:253], off
	v_lshl_add_u64 v[252:253], v[66:67], 0, v[242:243]
	global_load_dwordx4 v[220:223], v[252:253], off offset:256
	v_lshl_add_u64 v[252:253], v[86:87], 0, v[242:243]
	global_load_dwordx4 v[224:227], v[252:253], off
	v_lshl_add_u64 v[252:253], v[86:87], 0, v[242:243]
	global_load_dwordx4 v[228:231], v[252:253], off offset:256
	s_nop 0
	v_lshl_add_u64 v[252:253], v[104:105], 0, v[242:243]
	global_load_dwordx4 v[244:247], v[252:253], off
	v_lshl_add_u64 v[252:253], v[104:105], 0, v[242:243]
	global_load_dwordx4 v[248:251], v[252:253], off offset:256
	s_nop 0
	v_lshl_add_u64 v[94:95], s[34:35], 0, v[94:95]
	v_lshl_add_u64 v[94:95], v[140:141], 1, v[94:95]
	s_waitcnt vmcnt(7)
	v_permlane16_swap_b32 v208, v210
	v_permlane16_swap_b32 v209, v211
	v_lshlrev_b32_e32 v104, 16, v208
	v_and_b32_e32 v105, 0xffff0000, v208
	v_lshlrev_b32_e32 v96, 16, v209
	v_and_b32_e32 v97, 0xffff0000, v209
	s_waitcnt vmcnt(7)
	v_lshlrev_b32_e32 v106, 16, v210
	v_and_b32_e32 v107, 0xffff0000, v210
	v_lshlrev_b32_e32 v98, 16, v211
	v_and_b32_e32 v99, 0xffff0000, v211
	s_waitcnt vmcnt(6)
	v_permlane16_swap_b32 v212, v214
	v_permlane16_swap_b32 v213, v215
	v_lshlrev_b32_e32 v108, 16, v212
	v_and_b32_e32 v109, 0xffff0000, v212
	v_lshlrev_b32_e32 v100, 16, v213
	v_and_b32_e32 v101, 0xffff0000, v213
	s_waitcnt vmcnt(6)
	v_lshlrev_b32_e32 v110, 16, v214
	v_and_b32_e32 v111, 0xffff0000, v214
	v_pk_fma_f32 v[62:63], v[62:63], 0.5, v[96:97] op_sel_hi:[1,0,1]
	v_pk_fma_f32 v[60:61], v[60:61], 0.5, v[104:105] op_sel_hi:[1,0,1]
	v_pk_fma_f32 v[58:59], v[58:59], 0.5, v[98:99] op_sel_hi:[1,0,1]
	v_pk_fma_f32 v[56:57], v[56:57], 0.5, v[106:107] op_sel_hi:[1,0,1]
	v_lshlrev_b32_e32 v102, 16, v215
	v_and_b32_e32 v103, 0xffff0000, v215
	v_pk_fma_f32 v[54:55], v[54:55], 0.5, v[100:101] op_sel_hi:[1,0,1]
	v_pk_fma_f32 v[52:53], v[52:53], 0.5, v[108:109] op_sel_hi:[1,0,1]
	v_pk_fma_f32 v[96:97], v[48:49], 0.5, v[110:111] op_sel_hi:[1,0,1]
	v_mul_f32_e32 v98, v61, v61
	v_mul_f32_e32 v99, v63, v63
	v_cvt_pk_bf16_f32 v232, v60, v61
	v_cvt_pk_bf16_f32 v233, v62, v63
	v_mul_f32_e32 v61, v57, v57
	v_mul_f32_e32 v63, v59, v59
	v_pk_fma_f32 v[50:51], v[50:51], 0.5, v[102:103] op_sel_hi:[1,0,1]
	v_mul_f32_e32 v100, v53, v53
	v_mul_f32_e32 v101, v55, v55
	v_fmac_f32_e32 v98, v60, v60
	v_fmac_f32_e32 v99, v62, v62
	v_fmac_f32_e32 v61, v56, v56
	v_fmac_f32_e32 v63, v58, v58
	v_mul_f32_e32 v102, v97, v97
	v_mul_f32_e32 v103, v51, v51
	v_cvt_pk_bf16_f32 v234, v56, v57
	v_fmac_f32_e32 v100, v52, v52
	v_fmac_f32_e32 v101, v54, v54
	v_add_f32_e32 v49, v98, v99
	v_add_f32_e32 v56, v61, v63
	v_fmac_f32_e32 v102, v96, v96
	v_fmac_f32_e32 v103, v50, v50
	v_add_f32_e32 v57, v100, v101
	v_add_f32_e32 v49, v49, v56
	v_add_f32_e32 v49, v49, v57
	v_add_f32_e32 v56, v102, v103
	v_add_f32_e32 v56, v49, v56
	ds_bpermute_b32 v57, v178, v56
	v_cvt_pk_bf16_f32 v235, v58, v59
	s_nop 1
	v_permlane16_swap_b32 v232, v234
	v_permlane16_swap_b32 v233, v235
	v_lshl_add_u64 v[240:241], v[94:95], 0, v[242:243]
	global_store_dwordx4 v[240:241], v[232:235], off sc1
	v_cvt_pk_bf16_f32 v236, v52, v53
	v_cvt_pk_bf16_f32 v237, v54, v55
	s_waitcnt lgkmcnt(0)
	v_add_f32_e32 v48, v56, v57
	ds_bpermute_b32 v49, v179, v48
	v_cvt_pk_bf16_f32 v238, v96, v97
	v_cvt_pk_bf16_f32 v239, v50, v51
	s_nop 1
	v_permlane16_swap_b32 v236, v238
	v_permlane16_swap_b32 v237, v239
	v_lshl_add_u64 v[240:241], v[94:95], 0, v[242:243]
	global_store_dwordx4 v[240:241], v[236:239], off offset:256 sc1
	s_and_saveexec_b64 s[50:51], s[6:7]
	s_cbranch_execz .LBB0_273
	s_waitcnt lgkmcnt(0)
	v_add_f32_e32 v48, v48, v49
	global_atomic_add_f32 v[112:113], v48, off offset:512
.LBB0_273:
	s_or_b64 exec, exec, s[50:51]
	s_waitcnt vmcnt(3)
	v_permlane16_swap_b32 v244, v246
	v_permlane16_swap_b32 v245, v247
	v_lshlrev_b32_e32 v48, 16, v244
	s_waitcnt lgkmcnt(0)
	v_and_b32_e32 v49, 0xffff0000, v244
	v_lshlrev_b32_e32 v50, 16, v245
	v_and_b32_e32 v51, 0xffff0000, v245
	v_pk_fma_f32 v[46:47], v[46:47], 0.5, v[50:51] op_sel_hi:[1,0,1]
	v_pk_fma_f32 v[44:45], v[44:45], 0.5, v[48:49] op_sel_hi:[1,0,1]
	v_mul_f32_e32 v49, v47, v47
	v_mul_f32_e32 v48, v45, v45
	s_waitcnt vmcnt(3)
	v_lshlrev_b32_e32 v52, 16, v246
	v_and_b32_e32 v53, 0xffff0000, v246
	v_lshlrev_b32_e32 v54, 16, v247
	v_and_b32_e32 v55, 0xffff0000, v247
	v_fmac_f32_e32 v48, v44, v44
	v_fmac_f32_e32 v49, v46, v46
	v_cvt_pk_bf16_f32 v232, v44, v45
	v_cvt_pk_bf16_f32 v233, v46, v47
	v_lshl_add_u64 v[46:47], s[34:35], 0, v[84:85]
	v_lshl_add_u64 v[46:47], v[140:141], 1, v[46:47]
	v_pk_fma_f32 v[42:43], v[42:43], 0.5, v[54:55] op_sel_hi:[1,0,1]
	v_pk_fma_f32 v[40:41], v[40:41], 0.5, v[52:53] op_sel_hi:[1,0,1]
	s_waitcnt vmcnt(2)
	v_permlane16_swap_b32 v248, v250
	v_permlane16_swap_b32 v249, v251
	v_lshlrev_b32_e32 v56, 16, v248
	v_and_b32_e32 v57, 0xffff0000, v248
	v_lshlrev_b32_e32 v58, 16, v249
	v_and_b32_e32 v59, 0xffff0000, v249
	v_mul_f32_e32 v44, v41, v41
	v_mul_f32_e32 v45, v43, v43
	v_fmac_f32_e32 v44, v40, v40
	v_fmac_f32_e32 v45, v42, v42
	v_pk_fma_f32 v[38:39], v[38:39], 0.5, v[58:59] op_sel_hi:[1,0,1]
	v_pk_fma_f32 v[36:37], v[36:37], 0.5, v[56:57] op_sel_hi:[1,0,1]
	v_add_f32_e32 v44, v44, v45
	v_cvt_pk_bf16_f32 v234, v40, v41
	v_mul_f32_e32 v41, v37, v37
	v_mul_f32_e32 v45, v39, v39
	v_add_f32_e32 v48, v48, v49
	v_fmac_f32_e32 v41, v36, v36
	v_fmac_f32_e32 v45, v38, v38
	s_waitcnt vmcnt(2)
	v_lshlrev_b32_e32 v60, 16, v250
	v_and_b32_e32 v61, 0xffff0000, v250
	v_lshlrev_b32_e32 v62, 16, v251
	v_and_b32_e32 v63, 0xffff0000, v251
	v_add_f32_e32 v44, v48, v44
	v_add_f32_e32 v41, v41, v45
	v_add_f32_e32 v41, v44, v41
	v_pk_fma_f32 v[34:35], v[34:35], 0.5, v[62:63] op_sel_hi:[1,0,1]
	v_pk_fma_f32 v[44:45], v[32:33], 0.5, v[60:61] op_sel_hi:[1,0,1]
	v_mul_f32_e32 v33, v35, v35
	v_mul_f32_e32 v32, v45, v45
	v_fmac_f32_e32 v32, v44, v44
	v_fmac_f32_e32 v33, v34, v34
	v_add_f32_e32 v32, v32, v33
	v_add_f32_e32 v32, v41, v32
	ds_bpermute_b32 v33, v178, v32
	v_cvt_pk_bf16_f32 v235, v42, v43
	s_nop 1
	v_permlane16_swap_b32 v232, v234
	v_permlane16_swap_b32 v233, v235
	v_lshl_add_u64 v[240:241], v[46:47], 0, v[242:243]
	global_store_dwordx4 v[240:241], v[232:235], off sc1
	v_cvt_pk_bf16_f32 v236, v36, v37
	v_cvt_pk_bf16_f32 v237, v38, v39
	s_waitcnt lgkmcnt(0)
	v_add_f32_e32 v32, v32, v33
	ds_bpermute_b32 v33, v179, v32
	v_cvt_pk_bf16_f32 v238, v44, v45
	v_cvt_pk_bf16_f32 v239, v34, v35
	s_nop 1
	v_permlane16_swap_b32 v236, v238
	v_permlane16_swap_b32 v237, v239
	v_lshl_add_u64 v[240:241], v[46:47], 0, v[242:243]
	global_store_dwordx4 v[240:241], v[236:239], off offset:256 sc1
	s_and_saveexec_b64 s[50:51], s[6:7]
	s_cbranch_execz .LBB0_275
	s_waitcnt lgkmcnt(0)
	v_add_f32_e32 v32, v32, v33
	global_atomic_add_f32 v[112:113], v32, off offset:576
.LBB0_275:
	s_or_b64 exec, exec, s[50:51]
	v_permlane16_swap_b32 v216, v218
	v_permlane16_swap_b32 v217, v219
	v_lshlrev_b32_e32 v32, 16, v216
	s_waitcnt lgkmcnt(0)
	v_and_b32_e32 v33, 0xffff0000, v216
	v_lshlrev_b32_e32 v34, 16, v217
	v_and_b32_e32 v35, 0xffff0000, v217
	v_pk_fma_f32 v[30:31], v[30:31], 0.5, v[34:35] op_sel_hi:[1,0,1]
	v_pk_fma_f32 v[28:29], v[28:29], 0.5, v[32:33] op_sel_hi:[1,0,1]
	v_mul_f32_e32 v33, v31, v31
	v_mul_f32_e32 v32, v29, v29
	v_lshlrev_b32_e32 v36, 16, v218
	v_and_b32_e32 v37, 0xffff0000, v218
	v_lshlrev_b32_e32 v38, 16, v219
	v_and_b32_e32 v39, 0xffff0000, v219
	v_fmac_f32_e32 v32, v28, v28
	v_fmac_f32_e32 v33, v30, v30
	v_cvt_pk_bf16_f32 v232, v28, v29
	v_cvt_pk_bf16_f32 v233, v30, v31
	v_lshl_add_u64 v[30:31], s[34:35], 0, v[74:75]
	v_lshl_add_u64 v[30:31], v[140:141], 1, v[30:31]
	v_pk_fma_f32 v[26:27], v[26:27], 0.5, v[38:39] op_sel_hi:[1,0,1]
	v_pk_fma_f32 v[24:25], v[24:25], 0.5, v[36:37] op_sel_hi:[1,0,1]
	v_permlane16_swap_b32 v220, v222
	v_permlane16_swap_b32 v221, v223
	v_lshlrev_b32_e32 v40, 16, v220
	v_and_b32_e32 v41, 0xffff0000, v220
	v_lshlrev_b32_e32 v42, 16, v221
	v_and_b32_e32 v43, 0xffff0000, v221
	v_mul_f32_e32 v28, v25, v25
	v_mul_f32_e32 v29, v27, v27
	v_fmac_f32_e32 v28, v24, v24
	v_fmac_f32_e32 v29, v26, v26
	v_pk_fma_f32 v[22:23], v[22:23], 0.5, v[42:43] op_sel_hi:[1,0,1]
	v_pk_fma_f32 v[20:21], v[20:21], 0.5, v[40:41] op_sel_hi:[1,0,1]
	v_add_f32_e32 v28, v28, v29
	v_cvt_pk_bf16_f32 v234, v24, v25
	v_mul_f32_e32 v25, v21, v21
	v_mul_f32_e32 v29, v23, v23
	v_add_f32_e32 v32, v32, v33
	v_fmac_f32_e32 v25, v20, v20
	v_fmac_f32_e32 v29, v22, v22
	v_lshlrev_b32_e32 v44, 16, v222
	v_and_b32_e32 v45, 0xffff0000, v222
	v_lshlrev_b32_e32 v46, 16, v223
	v_and_b32_e32 v47, 0xffff0000, v223
	v_add_f32_e32 v28, v32, v28
	v_add_f32_e32 v25, v25, v29
	v_add_f32_e32 v25, v28, v25
	v_pk_fma_f32 v[18:19], v[18:19], 0.5, v[46:47] op_sel_hi:[1,0,1]
	v_pk_fma_f32 v[28:29], v[16:17], 0.5, v[44:45] op_sel_hi:[1,0,1]
	v_mul_f32_e32 v17, v19, v19
	v_mul_f32_e32 v16, v29, v29
	v_fmac_f32_e32 v16, v28, v28
	v_fmac_f32_e32 v17, v18, v18
	v_add_f32_e32 v16, v16, v17
	v_add_f32_e32 v16, v25, v16
	ds_bpermute_b32 v17, v178, v16
	v_cvt_pk_bf16_f32 v235, v26, v27
	s_nop 1
	v_permlane16_swap_b32 v232, v234
	v_permlane16_swap_b32 v233, v235
	v_lshl_add_u64 v[240:241], v[30:31], 0, v[242:243]
	global_store_dwordx4 v[240:241], v[232:235], off sc1
	v_cvt_pk_bf16_f32 v236, v20, v21
	v_cvt_pk_bf16_f32 v237, v22, v23
	s_waitcnt lgkmcnt(0)
	v_add_f32_e32 v16, v16, v17
	ds_bpermute_b32 v17, v179, v16
	v_cvt_pk_bf16_f32 v238, v28, v29
	v_cvt_pk_bf16_f32 v239, v18, v19
	s_nop 1
	v_permlane16_swap_b32 v236, v238
	v_permlane16_swap_b32 v237, v239
	v_lshl_add_u64 v[240:241], v[30:31], 0, v[242:243]
	global_store_dwordx4 v[240:241], v[236:239], off offset:256 sc1
	s_and_saveexec_b64 s[50:51], s[6:7]
	s_cbranch_execz .LBB0_277
	s_waitcnt lgkmcnt(0)
	v_add_f32_e32 v16, v16, v17
	global_atomic_add_f32 v[112:113], v16, off offset:640
.LBB0_277:
	s_or_b64 exec, exec, s[50:51]
	v_permlane16_swap_b32 v224, v226
	v_permlane16_swap_b32 v225, v227
	v_lshlrev_b32_e32 v16, 16, v224
	s_waitcnt lgkmcnt(0)
	v_and_b32_e32 v17, 0xffff0000, v224
	v_lshlrev_b32_e32 v18, 16, v225
	v_and_b32_e32 v19, 0xffff0000, v225
	v_pk_fma_f32 v[14:15], v[14:15], 0.5, v[18:19] op_sel_hi:[1,0,1]
	v_pk_fma_f32 v[12:13], v[12:13], 0.5, v[16:17] op_sel_hi:[1,0,1]
	v_mul_f32_e32 v17, v15, v15
	v_mul_f32_e32 v16, v13, v13
	v_lshlrev_b32_e32 v20, 16, v226
	v_and_b32_e32 v21, 0xffff0000, v226
	v_lshlrev_b32_e32 v22, 16, v227
	v_and_b32_e32 v23, 0xffff0000, v227
	v_fmac_f32_e32 v16, v12, v12
	v_fmac_f32_e32 v17, v14, v14
	v_cvt_pk_bf16_f32 v232, v12, v13
	v_cvt_pk_bf16_f32 v233, v14, v15
	v_lshl_add_u64 v[14:15], s[34:35], 0, v[64:65]
	v_lshl_add_u64 v[14:15], v[140:141], 1, v[14:15]
	v_pk_fma_f32 v[10:11], v[10:11], 0.5, v[22:23] op_sel_hi:[1,0,1]
	v_pk_fma_f32 v[8:9], v[8:9], 0.5, v[20:21] op_sel_hi:[1,0,1]
	v_permlane16_swap_b32 v228, v230
	v_permlane16_swap_b32 v229, v231
	v_lshlrev_b32_e32 v24, 16, v228
	v_and_b32_e32 v25, 0xffff0000, v228
	v_lshlrev_b32_e32 v26, 16, v229
	v_and_b32_e32 v27, 0xffff0000, v229
	v_mul_f32_e32 v12, v9, v9
	v_mul_f32_e32 v13, v11, v11
	v_fmac_f32_e32 v12, v8, v8
	v_fmac_f32_e32 v13, v10, v10
	v_pk_fma_f32 v[6:7], v[6:7], 0.5, v[26:27] op_sel_hi:[1,0,1]
	v_pk_fma_f32 v[4:5], v[4:5], 0.5, v[24:25] op_sel_hi:[1,0,1]
	v_add_f32_e32 v12, v12, v13
	v_cvt_pk_bf16_f32 v234, v8, v9
	v_mul_f32_e32 v9, v5, v5
	v_mul_f32_e32 v13, v7, v7
	v_add_f32_e32 v16, v16, v17
	v_fmac_f32_e32 v9, v4, v4
	v_fmac_f32_e32 v13, v6, v6
	v_lshlrev_b32_e32 v28, 16, v230
	v_and_b32_e32 v29, 0xffff0000, v230
	v_lshlrev_b32_e32 v30, 16, v231
	v_and_b32_e32 v31, 0xffff0000, v231
	v_add_f32_e32 v12, v16, v12
	v_add_f32_e32 v9, v9, v13
	v_add_f32_e32 v9, v12, v9
	v_pk_fma_f32 v[2:3], v[2:3], 0.5, v[30:31] op_sel_hi:[1,0,1]
	v_pk_fma_f32 v[12:13], v[0:1], 0.5, v[28:29] op_sel_hi:[1,0,1]
	v_mul_f32_e32 v1, v3, v3
	v_mul_f32_e32 v0, v13, v13
	v_fmac_f32_e32 v0, v12, v12
	v_fmac_f32_e32 v1, v2, v2
	v_add_f32_e32 v0, v0, v1
	v_add_f32_e32 v0, v9, v0
	ds_bpermute_b32 v1, v178, v0
	v_cvt_pk_bf16_f32 v235, v10, v11
	s_nop 1
	v_permlane16_swap_b32 v232, v234
	v_permlane16_swap_b32 v233, v235
	v_lshl_add_u64 v[240:241], v[14:15], 0, v[242:243]
	global_store_dwordx4 v[240:241], v[232:235], off sc1
	v_cvt_pk_bf16_f32 v236, v4, v5
	v_cvt_pk_bf16_f32 v237, v6, v7
	s_waitcnt lgkmcnt(0)
	v_add_f32_e32 v0, v0, v1
	ds_bpermute_b32 v1, v179, v0
	v_cvt_pk_bf16_f32 v238, v12, v13
	v_cvt_pk_bf16_f32 v239, v2, v3
	s_nop 1
	v_permlane16_swap_b32 v236, v238
	v_permlane16_swap_b32 v237, v239
	v_lshl_add_u64 v[240:241], v[14:15], 0, v[242:243]
	global_store_dwordx4 v[240:241], v[236:239], off offset:256 sc1
	s_and_saveexec_b64 s[50:51], s[6:7]
	s_cbranch_execz .LBB0_279
	s_waitcnt lgkmcnt(0)
	v_add_f32_e32 v0, v0, v1
	global_atomic_add_f32 v[112:113], v0, off offset:704

.LBB0_521:
	v_mbcnt_lo_u32_b32 v46, -1, 0
	v_mbcnt_hi_u32_b32 v46, -1, v46
	v_bfe_u32 v46, v46, 4, 1
	v_mul_u32_u24_e32 v46, 24, v46
	v_mov_b32_e32 v47, 0
	s_lshl_b32 s14, s70, 8
	s_or_b32 s14, s14, s57
	v_lshl_add_u32 v2, v159, 2, s14
	v_ashrrev_i32_e32 v3, 31, v2
	v_mov_b64_e32 v[0:1], s[52:53]
	v_mad_i64_i32 v[4:5], s[14:15], v158, s5, v[0:1]
	v_lshlrev_b64 v[2:3], 1, v[2:3]
	v_lshl_add_u64 v[4:5], v[4:5], 0, v[2:3]
	v_cvt_pk_bf16_f32 v28, v240, v241
	v_cvt_pk_bf16_f32 v29, v236, v237
	v_cvt_pk_bf16_f32 v30, v238, v239
	v_cvt_pk_bf16_f32 v31, v234, v235
	v_or_b32_e32 v8, 16, v158
	s_nop 1
	v_permlane16_swap_b32 v28, v30
	v_permlane16_swap_b32 v29, v31
	v_lshl_add_u64 v[44:45], v[4:5], 0, v[46:47]
	global_store_dwordx4 v[44:45], v[28:31], off sc1
	v_cvt_pk_bf16_f32 v40, v232, v233
	v_cvt_pk_bf16_f32 v41, v226, v227
	v_cvt_pk_bf16_f32 v42, v230, v231
	v_cvt_pk_bf16_f32 v43, v228, v229
	s_nop 1
	v_permlane16_swap_b32 v40, v42
	v_permlane16_swap_b32 v41, v43
	v_lshl_add_u64 v[44:45], v[4:5], 0, v[46:47]
	global_store_dwordx4 v[44:45], v[40:43], off offset:256 sc1
	v_mad_i64_i32 v[4:5], s[14:15], v8, s5, v[0:1]
	v_lshl_add_u64 v[4:5], v[4:5], 0, v[2:3]
	v_cvt_pk_bf16_f32 v28, v222, v223
	v_cvt_pk_bf16_f32 v29, v218, v219
	v_cvt_pk_bf16_f32 v30, v220, v221
	v_cvt_pk_bf16_f32 v31, v216, v217
	v_or_b32_e32 v9, 32, v158
	s_nop 1
	v_permlane16_swap_b32 v28, v30
	v_permlane16_swap_b32 v29, v31
	v_lshl_add_u64 v[44:45], v[4:5], 0, v[46:47]
	global_store_dwordx4 v[44:45], v[28:31], off sc1
	v_cvt_pk_bf16_f32 v40, v214, v215
	v_cvt_pk_bf16_f32 v41, v208, v209
	v_cvt_pk_bf16_f32 v42, v212, v213
	v_cvt_pk_bf16_f32 v43, v210, v211
	s_nop 1
	v_permlane16_swap_b32 v40, v42
	v_permlane16_swap_b32 v41, v43
	v_lshl_add_u64 v[44:45], v[4:5], 0, v[46:47]
	global_store_dwordx4 v[44:45], v[40:43], off offset:256 sc1
	v_mad_i64_i32 v[4:5], s[14:15], v9, s5, v[0:1]
	v_lshl_add_u64 v[4:5], v[4:5], 0, v[2:3]
	v_cvt_pk_bf16_f32 v28, v206, v207
	v_cvt_pk_bf16_f32 v29, v202, v203
	v_cvt_pk_bf16_f32 v30, v204, v205
	v_cvt_pk_bf16_f32 v31, v200, v201
	v_or_b32_e32 v10, 48, v158
	s_nop 1
	v_permlane16_swap_b32 v28, v30
	v_permlane16_swap_b32 v29, v31
	v_lshl_add_u64 v[44:45], v[4:5], 0, v[46:47]
	global_store_dwordx4 v[44:45], v[28:31], off sc1
	v_cvt_pk_bf16_f32 v40, v94, v95
	v_cvt_pk_bf16_f32 v41, v88, v89
	v_cvt_pk_bf16_f32 v42, v90, v91
	v_cvt_pk_bf16_f32 v43, v92, v93
	s_nop 1
	v_permlane16_swap_b32 v40, v42
	v_permlane16_swap_b32 v41, v43
	v_lshl_add_u64 v[44:45], v[4:5], 0, v[46:47]
	global_store_dwordx4 v[44:45], v[40:43], off offset:256 sc1
	v_mad_i64_i32 v[4:5], s[14:15], v10, s5, v[0:1]
	v_lshl_add_u64 v[4:5], v[4:5], 0, v[2:3]
	v_cvt_pk_bf16_f32 v28, v102, v103
	v_cvt_pk_bf16_f32 v29, v96, v97
	v_cvt_pk_bf16_f32 v30, v98, v99
	v_cvt_pk_bf16_f32 v31, v100, v101
	v_add_u32_e32 v11, 0x80, v158
	s_nop 1
	v_permlane16_swap_b32 v28, v30
	v_permlane16_swap_b32 v29, v31
	v_lshl_add_u64 v[44:45], v[4:5], 0, v[46:47]
	global_store_dwordx4 v[44:45], v[28:31], off sc1
	v_cvt_pk_bf16_f32 v40, v118, v119
	v_cvt_pk_bf16_f32 v41, v112, v113
	v_cvt_pk_bf16_f32 v42, v114, v115
	v_cvt_pk_bf16_f32 v43, v116, v117
	s_nop 1
	v_permlane16_swap_b32 v40, v42
	v_permlane16_swap_b32 v41, v43
	v_lshl_add_u64 v[44:45], v[4:5], 0, v[46:47]
	global_store_dwordx4 v[44:45], v[40:43], off offset:256 sc1
	v_mad_i64_i32 v[4:5], s[14:15], v11, s5, v[0:1]
	v_lshl_add_u64 v[4:5], v[4:5], 0, v[2:3]
	v_cvt_pk_bf16_f32 v28, v198, v199
	v_cvt_pk_bf16_f32 v29, v194, v195
	v_cvt_pk_bf16_f32 v30, v196, v197
	v_cvt_pk_bf16_f32 v31, v192, v193
	v_add_u32_e32 v12, 0x90, v158
	s_nop 1
	v_permlane16_swap_b32 v28, v30
	v_permlane16_swap_b32 v29, v31
	v_lshl_add_u64 v[44:45], v[4:5], 0, v[46:47]
	global_store_dwordx4 v[44:45], v[28:31], off sc1
	v_cvt_pk_bf16_f32 v40, v126, v127
	v_cvt_pk_bf16_f32 v41, v120, v121
	v_cvt_pk_bf16_f32 v42, v122, v123
	v_cvt_pk_bf16_f32 v43, v124, v125
	s_nop 1
	v_permlane16_swap_b32 v40, v42
	v_permlane16_swap_b32 v41, v43
	v_lshl_add_u64 v[44:45], v[4:5], 0, v[46:47]
	global_store_dwordx4 v[44:45], v[40:43], off offset:256 sc1
	v_mad_i64_i32 v[4:5], s[14:15], v12, s5, v[0:1]
	v_lshl_add_u64 v[4:5], v[4:5], 0, v[2:3]
	v_cvt_pk_bf16_f32 v28, v190, v191
	v_cvt_pk_bf16_f32 v29, v186, v187
	v_cvt_pk_bf16_f32 v30, v188, v189
	v_cvt_pk_bf16_f32 v31, v184, v185
	v_add_u32_e32 v13, 0xa0, v158
	s_nop 1
	v_permlane16_swap_b32 v28, v30
	v_permlane16_swap_b32 v29, v31
	v_lshl_add_u64 v[44:45], v[4:5], 0, v[46:47]
	global_store_dwordx4 v[44:45], v[28:31], off sc1
	v_cvt_pk_bf16_f32 v40, v134, v135
	v_cvt_pk_bf16_f32 v41, v128, v129
	v_cvt_pk_bf16_f32 v42, v130, v131
	v_cvt_pk_bf16_f32 v43, v132, v133
	s_nop 1
	v_permlane16_swap_b32 v40, v42
	v_permlane16_swap_b32 v41, v43
	v_lshl_add_u64 v[44:45], v[4:5], 0, v[46:47]
	global_store_dwordx4 v[44:45], v[40:43], off offset:256 sc1
	v_mad_i64_i32 v[4:5], s[14:15], v13, s5, v[0:1]
	v_lshl_add_u64 v[4:5], v[4:5], 0, v[2:3]
	v_cvt_pk_bf16_f32 v28, v182, v183
	v_cvt_pk_bf16_f32 v29, v178, v179
	v_add_u32_e32 v14, 0xb0, v158
	v_cvt_pk_bf16_f32 v30, v180, v181
	v_cvt_pk_bf16_f32 v31, v176, v177
	s_nop 1
	v_permlane16_swap_b32 v28, v30
	v_permlane16_swap_b32 v29, v31
	v_lshl_add_u64 v[44:45], v[4:5], 0, v[46:47]
	global_store_dwordx4 v[44:45], v[28:31], off sc1
	v_cvt_pk_bf16_f32 v40, v142, v143
	v_cvt_pk_bf16_f32 v41, v136, v137
	v_mad_i64_i32 v[0:1], s[14:15], v14, s5, v[0:1]
	v_cvt_pk_bf16_f32 v42, v138, v139
	v_cvt_pk_bf16_f32 v43, v140, v141
	s_nop 1
	v_permlane16_swap_b32 v40, v42
	v_permlane16_swap_b32 v41, v43
	v_lshl_add_u64 v[44:45], v[4:5], 0, v[46:47]
	global_store_dwordx4 v[44:45], v[40:43], off offset:256 sc1
	v_lshl_add_u64 v[0:1], v[0:1], 0, v[2:3]
	v_cvt_pk_bf16_f32 v28, v166, v167
	v_cvt_pk_bf16_f32 v29, v162, v163
	v_cvt_pk_bf16_f32 v30, v164, v165
	v_cvt_pk_bf16_f32 v31, v160, v161
	s_nop 1
	v_permlane16_swap_b32 v28, v30
	v_permlane16_swap_b32 v29, v31
	v_lshl_add_u64 v[44:45], v[0:1], 0, v[46:47]
	global_store_dwordx4 v[44:45], v[28:31], off sc1
	v_cvt_pk_bf16_f32 v40, v172, v173
	v_cvt_pk_bf16_f32 v41, v170, v171
	s_andn2_b64 vcc, exec, s[12:13]
	s_mov_b64 s[12:13], -1
	v_cvt_pk_bf16_f32 v42, v174, v175
	v_cvt_pk_bf16_f32 v43, v168, v169
	s_nop 1
	v_permlane16_swap_b32 v40, v42
	v_permlane16_swap_b32 v41, v43
	v_lshl_add_u64 v[44:45], v[0:1], 0, v[46:47]
	global_store_dwordx4 v[44:45], v[40:43], off offset:256 sc1
	s_cbranch_vccnz .LBB0_344
	s_and_b64 vcc, exec, s[6:7]
	s_cbranch_vccnz .LBB0_343
	s_barrier
	s_branch .LBB0_343

.LBB0_753:
	v_mbcnt_lo_u32_b32 v242, -1, 0
	v_mbcnt_hi_u32_b32 v242, -1, v242
	v_bfe_u32 v242, v242, 4, 1
	v_mul_u32_u24_e32 v242, 24, v242
	v_mov_b32_e32 v243, 0
	v_lshl_or_b32 v140, s42, 8, v186
	v_lshl_add_u32 v144, s40, 8, v182
	v_ashrrev_i32_e32 v141, 31, v140
	v_lshlrev_b64 v[190:191], 1, v[140:141]
	v_ashrrev_i32_e32 v145, 31, v144
	v_lshl_add_u64 v[142:143], s[34:35], 0, v[190:191]
	v_lshlrev_b64 v[192:193], 12, v[144:145]
	v_lshl_add_u64 v[146:147], v[142:143], 0, v[192:193]
	v_lshl_add_u64 v[252:253], v[146:147], 0, v[242:243]
	global_load_dwordx4 v[208:211], v[252:253], off
	v_lshl_add_u64 v[252:253], v[146:147], 0, v[242:243]
	global_load_dwordx4 v[212:215], v[252:253], off offset:256
	v_or_b32_e32 v162, 16, v144
	v_or_b32_e32 v150, 32, v144
	v_or_b32_e32 v146, 48, v144
	v_ashrrev_i32_e32 v163, 31, v162
	v_ashrrev_i32_e32 v151, 31, v150
	v_ashrrev_i32_e32 v147, 31, v146
	v_lshlrev_b64 v[172:173], 12, v[162:163]
	v_lshlrev_b64 v[160:161], 12, v[150:151]
	v_lshlrev_b64 v[148:149], 12, v[146:147]
	v_lshl_add_u64 v[152:153], v[142:143], 0, v[172:173]
	v_lshl_add_u64 v[154:155], v[142:143], 0, v[160:161]
	v_lshl_add_u64 v[202:203], v[142:143], 0, v[148:149]
	v_lshl_add_u64 v[252:253], v[152:153], 0, v[242:243]
	global_load_dwordx4 v[216:219], v[252:253], off
	v_lshl_add_u64 v[252:253], v[152:153], 0, v[242:243]
	global_load_dwordx4 v[220:223], v[252:253], off offset:256
	v_lshl_add_u64 v[252:253], v[154:155], 0, v[242:243]
	global_load_dwordx4 v[224:227], v[252:253], off
	v_lshl_add_u64 v[252:253], v[154:155], 0, v[242:243]
	global_load_dwordx4 v[228:231], v[252:253], off offset:256
	v_lshl_add_u64 v[252:253], v[202:203], 0, v[242:243]
	global_load_dwordx4 v[244:247], v[252:253], off
	s_nop 0
	v_lshl_add_u64 v[252:253], v[202:203], 0, v[242:243]
	global_load_dwordx4 v[248:251], v[252:253], off offset:256
	v_lshl_add_u64 v[192:193], s[34:35], 0, v[192:193]
	v_lshl_add_u64 v[190:191], v[192:193], 0, v[190:191]
	s_waitcnt vmcnt(0)
	v_permlane16_swap_b32 v208, v210
	v_permlane16_swap_b32 v209, v211
	v_lshlrev_b32_e32 v192, 16, v208
	v_and_b32_e32 v193, 0xffff0000, v208
	v_lshlrev_b32_e32 v194, 16, v209
	v_and_b32_e32 v195, 0xffff0000, v209
	v_lshlrev_b32_e32 v202, 16, v210
	v_and_b32_e32 v203, 0xffff0000, v210
	v_lshlrev_b32_e32 v196, 16, v211
	v_and_b32_e32 v197, 0xffff0000, v211
	v_permlane16_swap_b32 v212, v214
	v_permlane16_swap_b32 v213, v215
	v_lshlrev_b32_e32 v204, 16, v212
	v_and_b32_e32 v205, 0xffff0000, v212
	v_lshlrev_b32_e32 v198, 16, v213
	v_and_b32_e32 v199, 0xffff0000, v213
	v_lshlrev_b32_e32 v206, 16, v214
	v_and_b32_e32 v207, 0xffff0000, v214
	v_pk_add_f32 v[126:127], v[126:127], v[194:195]
	v_pk_add_f32 v[124:125], v[124:125], v[192:193]
	v_pk_add_f32 v[122:123], v[122:123], v[196:197]
	v_pk_add_f32 v[120:121], v[120:121], v[202:203]
	v_lshlrev_b32_e32 v200, 16, v215
	v_and_b32_e32 v201, 0xffff0000, v215
	v_pk_add_f32 v[118:119], v[118:119], v[198:199]
	v_pk_add_f32 v[116:117], v[116:117], v[204:205]
	v_pk_add_f32 v[192:193], v[112:113], v[206:207]
	v_mul_f32_e32 v194, v125, v125
	v_mul_f32_e32 v195, v127, v127
	v_cvt_pk_bf16_f32 v232, v124, v125
	v_cvt_pk_bf16_f32 v233, v126, v127
	v_mul_f32_e32 v125, v121, v121
	v_mul_f32_e32 v127, v123, v123
	v_pk_add_f32 v[114:115], v[114:115], v[200:201]
	v_mul_f32_e32 v196, v117, v117
	v_mul_f32_e32 v197, v119, v119
	v_fmac_f32_e32 v194, v124, v124
	v_fmac_f32_e32 v195, v126, v126
	v_fmac_f32_e32 v125, v120, v120
	v_fmac_f32_e32 v127, v122, v122
	v_mul_f32_e32 v198, v193, v193
	v_mul_f32_e32 v199, v115, v115
	v_cvt_pk_bf16_f32 v234, v120, v121
	v_fmac_f32_e32 v196, v116, v116
	v_fmac_f32_e32 v197, v118, v118
	v_add_f32_e32 v113, v194, v195
	v_add_f32_e32 v120, v125, v127
	v_fmac_f32_e32 v198, v192, v192
	v_fmac_f32_e32 v199, v114, v114
	v_add_f32_e32 v121, v196, v197
	v_add_f32_e32 v113, v113, v120
	v_add_f32_e32 v113, v113, v121
	v_add_f32_e32 v120, v198, v199
	v_add_f32_e32 v120, v113, v120
	ds_bpermute_b32 v121, v184, v120
	v_cvt_pk_bf16_f32 v235, v122, v123
	s_nop 1
	v_permlane16_swap_b32 v232, v234
	v_permlane16_swap_b32 v233, v235
	v_lshl_add_u64 v[240:241], v[190:191], 0, v[242:243]
	global_store_dwordx4 v[240:241], v[232:235], off sc1
	v_cvt_pk_bf16_f32 v236, v116, v117
	v_cvt_pk_bf16_f32 v237, v118, v119
	s_waitcnt lgkmcnt(0)
	v_add_f32_e32 v112, v120, v121
	ds_bpermute_b32 v113, v185, v112
	v_cvt_pk_bf16_f32 v238, v192, v193
	v_cvt_pk_bf16_f32 v239, v114, v115
	s_nop 1
	v_permlane16_swap_b32 v236, v238
	v_permlane16_swap_b32 v237, v239
	v_lshl_add_u64 v[240:241], v[190:191], 0, v[242:243]
	global_store_dwordx4 v[240:241], v[236:239], off offset:256 sc1
	s_and_saveexec_b64 s[40:41], s[8:9]
	s_cbranch_execz .LBB0_755
	v_lshl_add_u64 v[114:115], v[144:145], 2, s[12:13]
	s_waitcnt lgkmcnt(0)
	v_add_f32_e32 v112, v112, v113
	global_atomic_add_f32 v[114:115], v112, off
.LBB0_755:
	s_or_b64 exec, exec, s[40:41]
	v_permlane16_swap_b32 v216, v218
	v_permlane16_swap_b32 v217, v219
	v_lshlrev_b32_e32 v112, 16, v216
	s_waitcnt lgkmcnt(0)
	v_and_b32_e32 v113, 0xffff0000, v216
	v_lshlrev_b32_e32 v114, 16, v217
	v_and_b32_e32 v115, 0xffff0000, v217
	v_pk_add_f32 v[110:111], v[110:111], v[114:115]
	v_pk_add_f32 v[108:109], v[108:109], v[112:113]
	v_mul_f32_e32 v113, v111, v111
	v_mul_f32_e32 v112, v109, v109
	v_lshlrev_b32_e32 v116, 16, v218
	v_and_b32_e32 v117, 0xffff0000, v218
	v_lshlrev_b32_e32 v118, 16, v219
	v_and_b32_e32 v119, 0xffff0000, v219
	v_fmac_f32_e32 v112, v108, v108
	v_fmac_f32_e32 v113, v110, v110
	v_cvt_pk_bf16_f32 v232, v108, v109
	v_cvt_pk_bf16_f32 v233, v110, v111
	v_lshl_add_u64 v[110:111], s[34:35], 0, v[172:173]
	v_lshl_add_u64 v[110:111], v[140:141], 1, v[110:111]
	v_pk_add_f32 v[106:107], v[106:107], v[118:119]
	v_pk_add_f32 v[104:105], v[104:105], v[116:117]
	v_permlane16_swap_b32 v220, v222
	v_permlane16_swap_b32 v221, v223
	v_lshlrev_b32_e32 v120, 16, v220
	v_and_b32_e32 v121, 0xffff0000, v220
	v_lshlrev_b32_e32 v122, 16, v221
	v_and_b32_e32 v123, 0xffff0000, v221
	v_mul_f32_e32 v108, v105, v105
	v_mul_f32_e32 v109, v107, v107
	v_fmac_f32_e32 v108, v104, v104
	v_fmac_f32_e32 v109, v106, v106
	v_pk_add_f32 v[102:103], v[102:103], v[122:123]
	v_pk_add_f32 v[100:101], v[100:101], v[120:121]
	v_add_f32_e32 v108, v108, v109
	v_cvt_pk_bf16_f32 v234, v104, v105
	v_mul_f32_e32 v105, v101, v101
	v_mul_f32_e32 v109, v103, v103
	v_add_f32_e32 v112, v112, v113
	v_fmac_f32_e32 v105, v100, v100
	v_fmac_f32_e32 v109, v102, v102
	v_lshlrev_b32_e32 v124, 16, v222
	v_and_b32_e32 v125, 0xffff0000, v222
	v_lshlrev_b32_e32 v126, 16, v223
	v_and_b32_e32 v127, 0xffff0000, v223
	v_add_f32_e32 v108, v112, v108
	v_add_f32_e32 v105, v105, v109
	v_add_f32_e32 v105, v108, v105
	v_pk_add_f32 v[98:99], v[98:99], v[126:127]
	v_pk_add_f32 v[108:109], v[96:97], v[124:125]
	v_mul_f32_e32 v97, v99, v99
	v_mul_f32_e32 v96, v109, v109
	v_fmac_f32_e32 v96, v108, v108
	v_fmac_f32_e32 v97, v98, v98
	v_add_f32_e32 v96, v96, v97
	v_add_f32_e32 v96, v105, v96
	ds_bpermute_b32 v97, v184, v96
	v_cvt_pk_bf16_f32 v235, v106, v107
	s_nop 1
	v_permlane16_swap_b32 v232, v234
	v_permlane16_swap_b32 v233, v235
	v_lshl_add_u64 v[240:241], v[110:111], 0, v[242:243]
	global_store_dwordx4 v[240:241], v[232:235], off sc1
	v_cvt_pk_bf16_f32 v236, v100, v101
	v_cvt_pk_bf16_f32 v237, v102, v103
	s_waitcnt lgkmcnt(0)
	v_add_f32_e32 v96, v96, v97
	ds_bpermute_b32 v97, v185, v96
	v_cvt_pk_bf16_f32 v238, v108, v109
	v_cvt_pk_bf16_f32 v239, v98, v99
	s_nop 1
	v_permlane16_swap_b32 v236, v238
	v_permlane16_swap_b32 v237, v239
	v_lshl_add_u64 v[240:241], v[110:111], 0, v[242:243]
	global_store_dwordx4 v[240:241], v[236:239], off offset:256 sc1
	s_and_saveexec_b64 s[40:41], s[8:9]
	s_cbranch_execz .LBB0_757
	v_lshl_add_u64 v[98:99], v[162:163], 2, s[12:13]
	s_waitcnt lgkmcnt(0)
	v_add_f32_e32 v96, v96, v97
	global_atomic_add_f32 v[98:99], v96, off
.LBB0_757:
	s_or_b64 exec, exec, s[40:41]
	v_permlane16_swap_b32 v224, v226
	v_permlane16_swap_b32 v225, v227
	v_lshlrev_b32_e32 v96, 16, v224
	s_waitcnt lgkmcnt(0)
	v_and_b32_e32 v97, 0xffff0000, v224
	v_lshlrev_b32_e32 v98, 16, v225
	v_and_b32_e32 v99, 0xffff0000, v225
	v_pk_add_f32 v[94:95], v[94:95], v[98:99]
	v_pk_add_f32 v[92:93], v[92:93], v[96:97]
	v_mul_f32_e32 v97, v95, v95
	v_mul_f32_e32 v96, v93, v93
	v_lshlrev_b32_e32 v100, 16, v226
	v_and_b32_e32 v101, 0xffff0000, v226
	v_lshlrev_b32_e32 v102, 16, v227
	v_and_b32_e32 v103, 0xffff0000, v227
	v_fmac_f32_e32 v96, v92, v92
	v_fmac_f32_e32 v97, v94, v94
	v_cvt_pk_bf16_f32 v232, v92, v93
	v_cvt_pk_bf16_f32 v233, v94, v95
	v_lshl_add_u64 v[94:95], s[34:35], 0, v[160:161]
	v_lshl_add_u64 v[94:95], v[140:141], 1, v[94:95]
	v_pk_add_f32 v[90:91], v[90:91], v[102:103]
	v_pk_add_f32 v[88:89], v[88:89], v[100:101]
	v_permlane16_swap_b32 v228, v230
	v_permlane16_swap_b32 v229, v231
	v_lshlrev_b32_e32 v104, 16, v228
	v_and_b32_e32 v105, 0xffff0000, v228
	v_lshlrev_b32_e32 v106, 16, v229
	v_and_b32_e32 v107, 0xffff0000, v229
	v_mul_f32_e32 v92, v89, v89
	v_mul_f32_e32 v93, v91, v91
	v_fmac_f32_e32 v92, v88, v88
	v_fmac_f32_e32 v93, v90, v90
	v_pk_add_f32 v[86:87], v[86:87], v[106:107]
	v_pk_add_f32 v[84:85], v[84:85], v[104:105]
	v_add_f32_e32 v92, v92, v93
	v_cvt_pk_bf16_f32 v234, v88, v89
	v_mul_f32_e32 v89, v85, v85
	v_mul_f32_e32 v93, v87, v87
	v_add_f32_e32 v96, v96, v97
	v_fmac_f32_e32 v89, v84, v84
	v_fmac_f32_e32 v93, v86, v86
	v_lshlrev_b32_e32 v108, 16, v230
	v_and_b32_e32 v109, 0xffff0000, v230
	v_lshlrev_b32_e32 v110, 16, v231
	v_and_b32_e32 v111, 0xffff0000, v231
	v_add_f32_e32 v92, v96, v92
	v_add_f32_e32 v89, v89, v93
	v_add_f32_e32 v89, v92, v89
	v_pk_add_f32 v[82:83], v[82:83], v[110:111]
	v_pk_add_f32 v[92:93], v[80:81], v[108:109]
	v_mul_f32_e32 v81, v83, v83
	v_mul_f32_e32 v80, v93, v93
	v_fmac_f32_e32 v80, v92, v92
	v_fmac_f32_e32 v81, v82, v82
	v_add_f32_e32 v80, v80, v81
	v_add_f32_e32 v80, v89, v80
	ds_bpermute_b32 v81, v184, v80
	v_cvt_pk_bf16_f32 v235, v90, v91
	s_nop 1
	v_permlane16_swap_b32 v232, v234
	v_permlane16_swap_b32 v233, v235
	v_lshl_add_u64 v[240:241], v[94:95], 0, v[242:243]
	global_store_dwordx4 v[240:241], v[232:235], off sc1
	v_cvt_pk_bf16_f32 v236, v84, v85
	v_cvt_pk_bf16_f32 v237, v86, v87
	s_waitcnt lgkmcnt(0)
	v_add_f32_e32 v80, v80, v81
	ds_bpermute_b32 v81, v185, v80
	v_cvt_pk_bf16_f32 v238, v92, v93
	v_cvt_pk_bf16_f32 v239, v82, v83
	s_nop 1
	v_permlane16_swap_b32 v236, v238
	v_permlane16_swap_b32 v237, v239
	v_lshl_add_u64 v[240:241], v[94:95], 0, v[242:243]
	global_store_dwordx4 v[240:241], v[236:239], off offset:256 sc1
	s_and_saveexec_b64 s[40:41], s[8:9]
	s_cbranch_execz .LBB0_759
	v_lshl_add_u64 v[82:83], v[150:151], 2, s[12:13]
	s_waitcnt lgkmcnt(0)
	v_add_f32_e32 v80, v80, v81
	global_atomic_add_f32 v[82:83], v80, off
.LBB0_759:
	s_or_b64 exec, exec, s[40:41]
	v_permlane16_swap_b32 v244, v246
	v_permlane16_swap_b32 v245, v247
	v_lshlrev_b32_e32 v80, 16, v244
	s_waitcnt lgkmcnt(0)
	v_and_b32_e32 v81, 0xffff0000, v244
	v_lshlrev_b32_e32 v82, 16, v245
	v_and_b32_e32 v83, 0xffff0000, v245
	v_pk_add_f32 v[78:79], v[78:79], v[82:83]
	v_pk_add_f32 v[76:77], v[76:77], v[80:81]
	v_mul_f32_e32 v81, v79, v79
	v_mul_f32_e32 v80, v77, v77
	v_lshlrev_b32_e32 v84, 16, v246
	v_and_b32_e32 v85, 0xffff0000, v246
	v_lshlrev_b32_e32 v86, 16, v247
	v_and_b32_e32 v87, 0xffff0000, v247
	v_fmac_f32_e32 v80, v76, v76
	v_fmac_f32_e32 v81, v78, v78
	v_cvt_pk_bf16_f32 v232, v76, v77
	v_cvt_pk_bf16_f32 v233, v78, v79
	v_lshl_add_u64 v[78:79], s[34:35], 0, v[148:149]
	v_lshl_add_u64 v[78:79], v[140:141], 1, v[78:79]
	v_pk_add_f32 v[74:75], v[74:75], v[86:87]
	v_pk_add_f32 v[72:73], v[72:73], v[84:85]
	v_permlane16_swap_b32 v248, v250
	v_permlane16_swap_b32 v249, v251
	v_lshlrev_b32_e32 v88, 16, v248
	v_and_b32_e32 v89, 0xffff0000, v248
	v_lshlrev_b32_e32 v90, 16, v249
	v_and_b32_e32 v91, 0xffff0000, v249
	v_mul_f32_e32 v76, v73, v73
	v_mul_f32_e32 v77, v75, v75
	v_fmac_f32_e32 v76, v72, v72
	v_fmac_f32_e32 v77, v74, v74
	v_pk_add_f32 v[70:71], v[70:71], v[90:91]
	v_pk_add_f32 v[68:69], v[68:69], v[88:89]
	v_add_f32_e32 v76, v76, v77
	v_cvt_pk_bf16_f32 v234, v72, v73
	v_mul_f32_e32 v73, v69, v69
	v_mul_f32_e32 v77, v71, v71
	v_add_f32_e32 v80, v80, v81
	v_fmac_f32_e32 v73, v68, v68
	v_fmac_f32_e32 v77, v70, v70
	v_lshlrev_b32_e32 v92, 16, v250
	v_and_b32_e32 v93, 0xffff0000, v250
	v_lshlrev_b32_e32 v94, 16, v251
	v_and_b32_e32 v95, 0xffff0000, v251
	v_add_f32_e32 v76, v80, v76
	v_add_f32_e32 v73, v73, v77
	v_add_f32_e32 v73, v76, v73
	v_pk_add_f32 v[66:67], v[66:67], v[94:95]
	v_pk_add_f32 v[76:77], v[64:65], v[92:93]
	v_mul_f32_e32 v65, v67, v67
	v_mul_f32_e32 v64, v77, v77
	v_fmac_f32_e32 v64, v76, v76
	v_fmac_f32_e32 v65, v66, v66
	v_add_f32_e32 v64, v64, v65
	v_add_f32_e32 v64, v73, v64
	ds_bpermute_b32 v65, v184, v64
	v_cvt_pk_bf16_f32 v235, v74, v75
	s_nop 1
	v_permlane16_swap_b32 v232, v234
	v_permlane16_swap_b32 v233, v235
	v_lshl_add_u64 v[240:241], v[78:79], 0, v[242:243]
	global_store_dwordx4 v[240:241], v[232:235], off sc1
	v_cvt_pk_bf16_f32 v236, v68, v69
	v_cvt_pk_bf16_f32 v237, v70, v71
	s_waitcnt lgkmcnt(0)
	v_add_f32_e32 v64, v64, v65
	ds_bpermute_b32 v65, v185, v64
	v_cvt_pk_bf16_f32 v238, v76, v77
	v_cvt_pk_bf16_f32 v239, v66, v67
	s_nop 1
	v_permlane16_swap_b32 v236, v238
	v_permlane16_swap_b32 v237, v239
	v_lshl_add_u64 v[240:241], v[78:79], 0, v[242:243]
	global_store_dwordx4 v[240:241], v[236:239], off offset:256 sc1
	s_and_saveexec_b64 s[40:41], s[8:9]
	s_cbranch_execz .LBB0_761
	v_lshl_add_u64 v[66:67], v[146:147], 2, s[12:13]
	s_waitcnt lgkmcnt(0)
	v_add_f32_e32 v64, v64, v65
	global_atomic_add_f32 v[66:67], v64, off
.LBB0_761:
	s_or_b64 exec, exec, s[40:41]
	v_add_u32_e32 v90, 0x80, v144
	v_ashrrev_i32_e32 v91, 31, v90
	v_lshlrev_b64 v[102:103], 12, v[90:91]
	s_waitcnt lgkmcnt(0)
	v_lshl_add_u64 v[64:65], v[142:143], 0, v[102:103]
	v_lshl_add_u64 v[252:253], v[64:65], 0, v[242:243]
	global_load_dwordx4 v[208:211], v[252:253], off
	v_lshl_add_u64 v[252:253], v[64:65], 0, v[242:243]
	global_load_dwordx4 v[212:215], v[252:253], off offset:256
	v_add_u32_e32 v80, 0x90, v144
	v_add_u32_e32 v68, 0xa0, v144
	v_add_u32_e32 v64, 0xb0, v144
	v_ashrrev_i32_e32 v81, 31, v80
	v_ashrrev_i32_e32 v69, 31, v68
	v_ashrrev_i32_e32 v65, 31, v64
	v_lshlrev_b64 v[92:93], 12, v[80:81]
	v_lshlrev_b64 v[78:79], 12, v[68:69]
	v_lshlrev_b64 v[66:67], 12, v[64:65]
	v_lshl_add_u64 v[70:71], v[142:143], 0, v[92:93]
	v_lshl_add_u64 v[72:73], v[142:143], 0, v[78:79]
	v_lshl_add_u64 v[112:113], v[142:143], 0, v[66:67]
	v_lshl_add_u64 v[252:253], v[70:71], 0, v[242:243]
	global_load_dwordx4 v[216:219], v[252:253], off
	v_lshl_add_u64 v[252:253], v[70:71], 0, v[242:243]
	global_load_dwordx4 v[220:223], v[252:253], off offset:256
	v_lshl_add_u64 v[252:253], v[72:73], 0, v[242:243]
	global_load_dwordx4 v[224:227], v[252:253], off
	v_lshl_add_u64 v[252:253], v[72:73], 0, v[242:243]
	global_load_dwordx4 v[228:231], v[252:253], off offset:256
	v_lshl_add_u64 v[252:253], v[112:113], 0, v[242:243]
	global_load_dwordx4 v[244:247], v[252:253], off
	s_nop 0
	v_lshl_add_u64 v[252:253], v[112:113], 0, v[242:243]
	global_load_dwordx4 v[248:251], v[252:253], off offset:256
	v_lshl_add_u64 v[102:103], s[34:35], 0, v[102:103]
	v_lshl_add_u64 v[102:103], v[140:141], 1, v[102:103]
	s_waitcnt vmcnt(7)
	v_permlane16_swap_b32 v208, v210
	v_permlane16_swap_b32 v209, v211
	v_lshlrev_b32_e32 v112, 16, v208
	v_and_b32_e32 v113, 0xffff0000, v208
	v_lshlrev_b32_e32 v104, 16, v209
	v_and_b32_e32 v105, 0xffff0000, v209
	s_waitcnt vmcnt(7)
	v_lshlrev_b32_e32 v114, 16, v210
	v_and_b32_e32 v115, 0xffff0000, v210
	v_lshlrev_b32_e32 v106, 16, v211
	v_and_b32_e32 v107, 0xffff0000, v211
	s_waitcnt vmcnt(6)
	v_permlane16_swap_b32 v212, v214
	v_permlane16_swap_b32 v213, v215
	v_lshlrev_b32_e32 v116, 16, v212
	v_and_b32_e32 v117, 0xffff0000, v212
	v_lshlrev_b32_e32 v108, 16, v213
	v_and_b32_e32 v109, 0xffff0000, v213
	s_waitcnt vmcnt(6)
	v_lshlrev_b32_e32 v118, 16, v214
	v_and_b32_e32 v119, 0xffff0000, v214
	v_pk_add_f32 v[62:63], v[62:63], v[104:105]
	v_pk_add_f32 v[60:61], v[60:61], v[112:113]
	v_pk_add_f32 v[58:59], v[58:59], v[106:107]
	v_pk_add_f32 v[56:57], v[56:57], v[114:115]
	v_lshlrev_b32_e32 v110, 16, v215
	v_and_b32_e32 v111, 0xffff0000, v215
	v_pk_add_f32 v[54:55], v[54:55], v[108:109]
	v_pk_add_f32 v[52:53], v[52:53], v[116:117]
	v_pk_add_f32 v[104:105], v[48:49], v[118:119]
	v_mul_f32_e32 v106, v61, v61
	v_mul_f32_e32 v107, v63, v63
	v_cvt_pk_bf16_f32 v232, v60, v61
	v_cvt_pk_bf16_f32 v233, v62, v63
	v_mul_f32_e32 v61, v57, v57
	v_mul_f32_e32 v63, v59, v59
	v_pk_add_f32 v[50:51], v[50:51], v[110:111]
	v_mul_f32_e32 v108, v53, v53
	v_mul_f32_e32 v109, v55, v55
	v_fmac_f32_e32 v106, v60, v60
	v_fmac_f32_e32 v107, v62, v62
	v_fmac_f32_e32 v61, v56, v56
	v_fmac_f32_e32 v63, v58, v58
	v_mul_f32_e32 v110, v105, v105
	v_mul_f32_e32 v111, v51, v51
	v_cvt_pk_bf16_f32 v234, v56, v57
	v_fmac_f32_e32 v108, v52, v52
	v_fmac_f32_e32 v109, v54, v54
	v_add_f32_e32 v49, v106, v107
	v_add_f32_e32 v56, v61, v63
	v_fmac_f32_e32 v110, v104, v104
	v_fmac_f32_e32 v111, v50, v50
	v_add_f32_e32 v57, v108, v109
	v_add_f32_e32 v49, v49, v56
	v_add_f32_e32 v49, v49, v57
	v_add_f32_e32 v56, v110, v111
	v_add_f32_e32 v56, v49, v56
	ds_bpermute_b32 v57, v184, v56
	v_cvt_pk_bf16_f32 v235, v58, v59
	s_nop 1
	v_permlane16_swap_b32 v232, v234
	v_permlane16_swap_b32 v233, v235
	v_lshl_add_u64 v[240:241], v[102:103], 0, v[242:243]
	global_store_dwordx4 v[240:241], v[232:235], off sc1
	v_cvt_pk_bf16_f32 v236, v52, v53
	v_cvt_pk_bf16_f32 v237, v54, v55
	s_waitcnt lgkmcnt(0)
	v_add_f32_e32 v48, v56, v57
	ds_bpermute_b32 v49, v185, v48
	v_cvt_pk_bf16_f32 v238, v104, v105
	v_cvt_pk_bf16_f32 v239, v50, v51
	s_nop 1
	v_permlane16_swap_b32 v236, v238
	v_permlane16_swap_b32 v237, v239
	v_lshl_add_u64 v[240:241], v[102:103], 0, v[242:243]
	global_store_dwordx4 v[240:241], v[236:239], off offset:256 sc1
	s_and_saveexec_b64 s[40:41], s[8:9]
	s_cbranch_execz .LBB0_763
	v_lshl_add_u64 v[50:51], v[90:91], 2, s[12:13]
	s_waitcnt lgkmcnt(0)
	v_add_f32_e32 v48, v48, v49
	global_atomic_add_f32 v[50:51], v48, off
.LBB0_763:
	s_or_b64 exec, exec, s[40:41]
	s_waitcnt vmcnt(7)
	v_permlane16_swap_b32 v216, v218
	v_permlane16_swap_b32 v217, v219
	v_lshlrev_b32_e32 v48, 16, v216
	s_waitcnt lgkmcnt(0)
	v_and_b32_e32 v49, 0xffff0000, v216
	v_lshlrev_b32_e32 v50, 16, v217
	v_and_b32_e32 v51, 0xffff0000, v217
	v_pk_add_f32 v[46:47], v[46:47], v[50:51]
	v_pk_add_f32 v[44:45], v[44:45], v[48:49]
	v_mul_f32_e32 v49, v47, v47
	v_mul_f32_e32 v48, v45, v45
	s_waitcnt vmcnt(7)
	v_lshlrev_b32_e32 v52, 16, v218
	v_and_b32_e32 v53, 0xffff0000, v218
	v_lshlrev_b32_e32 v54, 16, v219
	v_and_b32_e32 v55, 0xffff0000, v219
	v_fmac_f32_e32 v48, v44, v44
	v_fmac_f32_e32 v49, v46, v46
	v_cvt_pk_bf16_f32 v232, v44, v45
	v_cvt_pk_bf16_f32 v233, v46, v47
	v_lshl_add_u64 v[46:47], s[34:35], 0, v[92:93]
	v_lshl_add_u64 v[46:47], v[140:141], 1, v[46:47]
	v_pk_add_f32 v[42:43], v[42:43], v[54:55]
	v_pk_add_f32 v[40:41], v[40:41], v[52:53]
	s_waitcnt vmcnt(6)
	v_permlane16_swap_b32 v220, v222
	v_permlane16_swap_b32 v221, v223
	v_lshlrev_b32_e32 v56, 16, v220
	v_and_b32_e32 v57, 0xffff0000, v220
	v_lshlrev_b32_e32 v58, 16, v221
	v_and_b32_e32 v59, 0xffff0000, v221
	v_mul_f32_e32 v44, v41, v41
	v_mul_f32_e32 v45, v43, v43
	v_fmac_f32_e32 v44, v40, v40
	v_fmac_f32_e32 v45, v42, v42
	v_pk_add_f32 v[38:39], v[38:39], v[58:59]
	v_pk_add_f32 v[36:37], v[36:37], v[56:57]
	v_add_f32_e32 v44, v44, v45
	v_cvt_pk_bf16_f32 v234, v40, v41
	v_mul_f32_e32 v41, v37, v37
	v_mul_f32_e32 v45, v39, v39
	v_add_f32_e32 v48, v48, v49
	v_fmac_f32_e32 v41, v36, v36
	v_fmac_f32_e32 v45, v38, v38
	s_waitcnt vmcnt(6)
	v_lshlrev_b32_e32 v60, 16, v222
	v_and_b32_e32 v61, 0xffff0000, v222
	v_lshlrev_b32_e32 v62, 16, v223
	v_and_b32_e32 v63, 0xffff0000, v223
	v_add_f32_e32 v44, v48, v44
	v_add_f32_e32 v41, v41, v45
	v_add_f32_e32 v41, v44, v41
	v_pk_add_f32 v[34:35], v[34:35], v[62:63]
	v_pk_add_f32 v[44:45], v[32:33], v[60:61]
	v_mul_f32_e32 v33, v35, v35
	v_mul_f32_e32 v32, v45, v45
	v_fmac_f32_e32 v32, v44, v44
	v_fmac_f32_e32 v33, v34, v34
	v_add_f32_e32 v32, v32, v33
	v_add_f32_e32 v32, v41, v32
	ds_bpermute_b32 v33, v184, v32
	v_cvt_pk_bf16_f32 v235, v42, v43
	s_nop 1
	v_permlane16_swap_b32 v232, v234
	v_permlane16_swap_b32 v233, v235
	v_lshl_add_u64 v[240:241], v[46:47], 0, v[242:243]
	global_store_dwordx4 v[240:241], v[232:235], off sc1
	v_cvt_pk_bf16_f32 v236, v36, v37
	v_cvt_pk_bf16_f32 v237, v38, v39
	s_waitcnt lgkmcnt(0)
	v_add_f32_e32 v32, v32, v33
	ds_bpermute_b32 v33, v185, v32
	v_cvt_pk_bf16_f32 v238, v44, v45
	v_cvt_pk_bf16_f32 v239, v34, v35
	s_nop 1
	v_permlane16_swap_b32 v236, v238
	v_permlane16_swap_b32 v237, v239
	v_lshl_add_u64 v[240:241], v[46:47], 0, v[242:243]
	global_store_dwordx4 v[240:241], v[236:239], off offset:256 sc1
	s_and_saveexec_b64 s[40:41], s[8:9]
	s_cbranch_execz .LBB0_765
	v_lshl_add_u64 v[34:35], v[80:81], 2, s[12:13]
	s_waitcnt lgkmcnt(0)
	v_add_f32_e32 v32, v32, v33
	global_atomic_add_f32 v[34:35], v32, off
.LBB0_765:
	s_or_b64 exec, exec, s[40:41]
	s_waitcnt vmcnt(7)
	v_permlane16_swap_b32 v224, v226
	v_permlane16_swap_b32 v225, v227
	v_lshlrev_b32_e32 v32, 16, v224
	s_waitcnt lgkmcnt(0)
	v_and_b32_e32 v33, 0xffff0000, v224
	v_lshlrev_b32_e32 v34, 16, v225
	v_and_b32_e32 v35, 0xffff0000, v225
	v_pk_add_f32 v[30:31], v[30:31], v[34:35]
	v_pk_add_f32 v[28:29], v[28:29], v[32:33]
	v_mul_f32_e32 v33, v31, v31
	v_mul_f32_e32 v32, v29, v29
	s_waitcnt vmcnt(7)
	v_lshlrev_b32_e32 v36, 16, v226
	v_and_b32_e32 v37, 0xffff0000, v226
	v_lshlrev_b32_e32 v38, 16, v227
	v_and_b32_e32 v39, 0xffff0000, v227
	v_fmac_f32_e32 v32, v28, v28
	v_fmac_f32_e32 v33, v30, v30
	v_cvt_pk_bf16_f32 v232, v28, v29
	v_cvt_pk_bf16_f32 v233, v30, v31
	v_lshl_add_u64 v[30:31], s[34:35], 0, v[78:79]
	v_lshl_add_u64 v[30:31], v[140:141], 1, v[30:31]
	v_pk_add_f32 v[26:27], v[26:27], v[38:39]
	v_pk_add_f32 v[24:25], v[24:25], v[36:37]
	s_waitcnt vmcnt(6)
	v_permlane16_swap_b32 v228, v230
	v_permlane16_swap_b32 v229, v231
	v_lshlrev_b32_e32 v40, 16, v228
	v_and_b32_e32 v41, 0xffff0000, v228
	v_lshlrev_b32_e32 v42, 16, v229
	v_and_b32_e32 v43, 0xffff0000, v229
	v_mul_f32_e32 v28, v25, v25
	v_mul_f32_e32 v29, v27, v27
	v_fmac_f32_e32 v28, v24, v24
	v_fmac_f32_e32 v29, v26, v26
	v_pk_add_f32 v[22:23], v[22:23], v[42:43]
	v_pk_add_f32 v[20:21], v[20:21], v[40:41]
	v_add_f32_e32 v28, v28, v29
	v_cvt_pk_bf16_f32 v234, v24, v25
	v_mul_f32_e32 v25, v21, v21
	v_mul_f32_e32 v29, v23, v23
	v_add_f32_e32 v32, v32, v33
	v_fmac_f32_e32 v25, v20, v20
	v_fmac_f32_e32 v29, v22, v22
	s_waitcnt vmcnt(6)
	v_lshlrev_b32_e32 v44, 16, v230
	v_and_b32_e32 v45, 0xffff0000, v230
	v_lshlrev_b32_e32 v46, 16, v231
	v_and_b32_e32 v47, 0xffff0000, v231
	v_add_f32_e32 v28, v32, v28
	v_add_f32_e32 v25, v25, v29
	v_add_f32_e32 v25, v28, v25
	v_pk_add_f32 v[18:19], v[18:19], v[46:47]
	v_pk_add_f32 v[28:29], v[16:17], v[44:45]
	v_mul_f32_e32 v17, v19, v19
	v_mul_f32_e32 v16, v29, v29
	v_fmac_f32_e32 v16, v28, v28
	v_fmac_f32_e32 v17, v18, v18
	v_add_f32_e32 v16, v16, v17
	v_add_f32_e32 v16, v25, v16
	ds_bpermute_b32 v17, v184, v16
	v_cvt_pk_bf16_f32 v235, v26, v27
	s_nop 1
	v_permlane16_swap_b32 v232, v234
	v_permlane16_swap_b32 v233, v235
	v_lshl_add_u64 v[240:241], v[30:31], 0, v[242:243]
	global_store_dwordx4 v[240:241], v[232:235], off sc1
	v_cvt_pk_bf16_f32 v236, v20, v21
	v_cvt_pk_bf16_f32 v237, v22, v23
	s_waitcnt lgkmcnt(0)
	v_add_f32_e32 v16, v16, v17
	ds_bpermute_b32 v17, v185, v16
	v_cvt_pk_bf16_f32 v238, v28, v29
	v_cvt_pk_bf16_f32 v239, v18, v19
	s_nop 1
	v_permlane16_swap_b32 v236, v238
	v_permlane16_swap_b32 v237, v239
	v_lshl_add_u64 v[240:241], v[30:31], 0, v[242:243]
	global_store_dwordx4 v[240:241], v[236:239], off offset:256 sc1
	s_and_saveexec_b64 s[40:41], s[8:9]
	s_cbranch_execz .LBB0_767
	v_lshl_add_u64 v[18:19], v[68:69], 2, s[12:13]
	s_waitcnt lgkmcnt(0)
	v_add_f32_e32 v16, v16, v17
	global_atomic_add_f32 v[18:19], v16, off
.LBB0_767:
	s_or_b64 exec, exec, s[40:41]
	s_waitcnt vmcnt(7)
	v_permlane16_swap_b32 v244, v246
	v_permlane16_swap_b32 v245, v247
	v_lshlrev_b32_e32 v16, 16, v244
	s_waitcnt lgkmcnt(0)
	v_and_b32_e32 v17, 0xffff0000, v244
	v_lshlrev_b32_e32 v18, 16, v245
	v_and_b32_e32 v19, 0xffff0000, v245
	v_pk_add_f32 v[14:15], v[14:15], v[18:19]
	v_pk_add_f32 v[12:13], v[12:13], v[16:17]
	v_mul_f32_e32 v17, v15, v15
	v_mul_f32_e32 v16, v13, v13
	s_waitcnt vmcnt(7)
	v_lshlrev_b32_e32 v20, 16, v246
	v_and_b32_e32 v21, 0xffff0000, v246
	v_lshlrev_b32_e32 v22, 16, v247
	v_and_b32_e32 v23, 0xffff0000, v247
	v_fmac_f32_e32 v16, v12, v12
	v_fmac_f32_e32 v17, v14, v14
	v_cvt_pk_bf16_f32 v232, v12, v13
	v_cvt_pk_bf16_f32 v233, v14, v15
	v_lshl_add_u64 v[14:15], s[34:35], 0, v[66:67]
	v_lshl_add_u64 v[14:15], v[140:141], 1, v[14:15]
	v_pk_add_f32 v[10:11], v[10:11], v[22:23]
	v_pk_add_f32 v[8:9], v[8:9], v[20:21]
	s_waitcnt vmcnt(6)
	v_permlane16_swap_b32 v248, v250
	v_permlane16_swap_b32 v249, v251
	v_lshlrev_b32_e32 v24, 16, v248
	v_and_b32_e32 v25, 0xffff0000, v248
	v_lshlrev_b32_e32 v26, 16, v249
	v_and_b32_e32 v27, 0xffff0000, v249
	v_mul_f32_e32 v12, v9, v9
	v_mul_f32_e32 v13, v11, v11
	v_fmac_f32_e32 v12, v8, v8
	v_fmac_f32_e32 v13, v10, v10
	v_pk_add_f32 v[6:7], v[6:7], v[26:27]
	v_pk_add_f32 v[4:5], v[4:5], v[24:25]
	v_add_f32_e32 v12, v12, v13
	v_cvt_pk_bf16_f32 v234, v8, v9
	v_mul_f32_e32 v9, v5, v5
	v_mul_f32_e32 v13, v7, v7
	v_add_f32_e32 v16, v16, v17
	v_fmac_f32_e32 v9, v4, v4
	v_fmac_f32_e32 v13, v6, v6
	s_waitcnt vmcnt(6)
	v_lshlrev_b32_e32 v28, 16, v250
	v_and_b32_e32 v29, 0xffff0000, v250
	v_lshlrev_b32_e32 v30, 16, v251
	v_and_b32_e32 v31, 0xffff0000, v251
	v_add_f32_e32 v12, v16, v12
	v_add_f32_e32 v9, v9, v13
	v_add_f32_e32 v9, v12, v9
	v_pk_add_f32 v[2:3], v[2:3], v[30:31]
	v_pk_add_f32 v[12:13], v[0:1], v[28:29]
	v_mul_f32_e32 v1, v3, v3
	v_mul_f32_e32 v0, v13, v13
	v_fmac_f32_e32 v0, v12, v12
	v_fmac_f32_e32 v1, v2, v2
	v_add_f32_e32 v0, v0, v1
	v_add_f32_e32 v0, v9, v0
	ds_bpermute_b32 v1, v184, v0
	v_cvt_pk_bf16_f32 v235, v10, v11
	s_nop 1
	v_permlane16_swap_b32 v232, v234
	v_permlane16_swap_b32 v233, v235
	v_lshl_add_u64 v[240:241], v[14:15], 0, v[242:243]
	global_store_dwordx4 v[240:241], v[232:235], off sc1
	v_cvt_pk_bf16_f32 v236, v4, v5
	v_cvt_pk_bf16_f32 v237, v6, v7
	s_waitcnt lgkmcnt(0)
	v_add_f32_e32 v0, v0, v1
	ds_bpermute_b32 v1, v185, v0
	v_cvt_pk_bf16_f32 v238, v12, v13
	v_cvt_pk_bf16_f32 v239, v2, v3
	s_nop 1
	v_permlane16_swap_b32 v236, v238
	v_permlane16_swap_b32 v237, v239
	v_lshl_add_u64 v[240:241], v[14:15], 0, v[242:243]
	global_store_dwordx4 v[240:241], v[236:239], off offset:256 sc1
	s_and_saveexec_b64 s[40:41], s[8:9]
	s_cbranch_execz .LBB0_769
	v_lshl_add_u64 v[2:3], v[64:65], 2, s[12:13]
	s_waitcnt lgkmcnt(0)
	v_add_f32_e32 v0, v0, v1
	global_atomic_add_f32 v[2:3], v0, off
